# lever 2 prologue de-serialisation: conv-weight LDS preload issues its 31 loads together then one wait (was 16 serialized load-wait-write pairs)
# speedup vs baseline: 1.0006x; 1.0006x over previous
; #define LAS __attribute__((address_space(3)))
; __global__ void __launch_bounds__(512, 2) fwd_megakernel(Params p_) {
;     ...
;         if (PHM & 8)
;         {
;             TID_VARS
;             KARGS
;             { LAS float* WD0 = (LAS float*)lds; const float* wdw = p->in[I_WDW] + (size_t)l * 31 * 512;
;               for (int e = tid; e < 31 * 512; e += 512) WD0[e] = wdw[e]; }
.LBB0_291:
	s_or_b64 exec, exec, s[38:39]
	v_readlane_b32 s0, v253, 0
	v_mov_b32_e32 v48, v246
	v_readlane_b32 s1, v253, 1
	s_waitcnt lgkmcnt(0)
	s_barrier
	v_readlane_b32 s101, v253, 7
	s_nop 0
	s_bfe_u32 s101, s101, 0x10003
	s_movk_i32 s2, 0x3e00
	v_writelane_b32 v255, s0, 10
	s_load_dwordx2 s[6:7], s[0:1], 0xd0
	v_ashrrev_i32_e32 v49, 31, v48
	v_writelane_b32 v255, s1, 11
	v_readfirstlane_b32 s0, v48
	v_cmp_gt_i32_e32 vcc, s2, v48
	s_nop 0
	v_writelane_b32 v255, s0, 12
	s_and_saveexec_b64 s[8:9], vcc
	s_cbranch_execz .LBB0_306
	v_readlane_b32 s0, v255, 10
	v_readlane_b32 s1, v255, 11
	s_nop 3
	s_load_dwordx2 s[10:11], s[0:1], 0x68
	v_readlane_b32 s0, v255, 6
	s_mul_i32 s3, s0, 0xf800
	s_mul_hi_u32 s2, s0, 0xf800
	v_lshlrev_b32_e32 v0, 2, v48
	s_waitcnt lgkmcnt(0)
	s_add_u32 s14, s10, s3
	s_addc_u32 s15, s11, s2
	global_load_dword v1, v0, s[14:15]
	global_load_dword v2, v0, s[14:15] offset:2048
	s_add_u32 s14, s14, 0x1000
	s_addc_u32 s15, s15, 0
	global_load_dword v3, v0, s[14:15]
	global_load_dword v4, v0, s[14:15] offset:2048
	s_add_u32 s14, s14, 0x1000
	s_addc_u32 s15, s15, 0
	global_load_dword v5, v0, s[14:15]
	global_load_dword v6, v0, s[14:15] offset:2048
	s_add_u32 s14, s14, 0x1000
	s_addc_u32 s15, s15, 0
	global_load_dword v7, v0, s[14:15]
	global_load_dword v8, v0, s[14:15] offset:2048
	s_add_u32 s14, s14, 0x1000
	s_addc_u32 s15, s15, 0
	global_load_dword v9, v0, s[14:15]
	global_load_dword v10, v0, s[14:15] offset:2048
	s_add_u32 s14, s14, 0x1000
	s_addc_u32 s15, s15, 0
	global_load_dword v11, v0, s[14:15]
	global_load_dword v12, v0, s[14:15] offset:2048
	s_add_u32 s14, s14, 0x1000
	s_addc_u32 s15, s15, 0
	global_load_dword v13, v0, s[14:15]
	global_load_dword v14, v0, s[14:15] offset:2048
	s_add_u32 s14, s14, 0x1000
	s_addc_u32 s15, s15, 0
	global_load_dword v15, v0, s[14:15]
	global_load_dword v16, v0, s[14:15] offset:2048
	s_add_u32 s14, s14, 0x1000
	s_addc_u32 s15, s15, 0
	global_load_dword v17, v0, s[14:15]
	global_load_dword v18, v0, s[14:15] offset:2048
	s_add_u32 s14, s14, 0x1000
	s_addc_u32 s15, s15, 0
	global_load_dword v19, v0, s[14:15]
	global_load_dword v20, v0, s[14:15] offset:2048
	s_add_u32 s14, s14, 0x1000
	s_addc_u32 s15, s15, 0
	global_load_dword v21, v0, s[14:15]
	global_load_dword v22, v0, s[14:15] offset:2048
	s_add_u32 s14, s14, 0x1000
	s_addc_u32 s15, s15, 0
	global_load_dword v23, v0, s[14:15]
	global_load_dword v24, v0, s[14:15] offset:2048
	s_add_u32 s14, s14, 0x1000
	s_addc_u32 s15, s15, 0
	global_load_dword v25, v0, s[14:15]
	global_load_dword v26, v0, s[14:15] offset:2048
	s_add_u32 s14, s14, 0x1000
	s_addc_u32 s15, s15, 0
	global_load_dword v27, v0, s[14:15]
	global_load_dword v28, v0, s[14:15] offset:2048
	s_add_u32 s14, s14, 0x1000
	s_addc_u32 s15, s15, 0
	global_load_dword v29, v0, s[14:15]
	global_load_dword v30, v0, s[14:15] offset:2048
	s_add_u32 s14, s14, 0x1000
	s_addc_u32 s15, s15, 0
	global_load_dword v31, v0, s[14:15]
	s_waitcnt vmcnt(0)
	ds_write_b32 v0, v1
	ds_write_b32 v0, v2 offset:2048
	ds_write_b32 v0, v3 offset:4096
	ds_write_b32 v0, v4 offset:6144
	ds_write_b32 v0, v5 offset:8192
	ds_write_b32 v0, v6 offset:10240
	ds_write_b32 v0, v7 offset:12288
	ds_write_b32 v0, v8 offset:14336
	ds_write_b32 v0, v9 offset:16384
	ds_write_b32 v0, v10 offset:18432
	ds_write_b32 v0, v11 offset:20480
	ds_write_b32 v0, v12 offset:22528
	ds_write_b32 v0, v13 offset:24576
	ds_write_b32 v0, v14 offset:26624
	ds_write_b32 v0, v15 offset:28672
	ds_write_b32 v0, v16 offset:30720
	ds_write_b32 v0, v17 offset:32768
	ds_write_b32 v0, v18 offset:34816
	ds_write_b32 v0, v19 offset:36864
	ds_write_b32 v0, v20 offset:38912
	ds_write_b32 v0, v21 offset:40960
	ds_write_b32 v0, v22 offset:43008
	ds_write_b32 v0, v23 offset:45056
	ds_write_b32 v0, v24 offset:47104
	ds_write_b32 v0, v25 offset:49152
	ds_write_b32 v0, v26 offset:51200
	ds_write_b32 v0, v27 offset:53248
	ds_write_b32 v0, v28 offset:55296
	ds_write_b32 v0, v29 offset:57344
	ds_write_b32 v0, v30 offset:59392
	ds_write_b32 v0, v31 offset:61440
